# NSA selected branch: tile 0 (always block 0) loaded before the top-16 selection
# speedup vs baseline: 1.0003x; 1.0003x over previous
; DI unsigned cvtpk(float lo, float hi) { f32x2_t v = {lo, hi}; bf16x2_t b = __builtin_convertvector(v, bf16x2_t); return __builtin_bit_cast(unsigned, b); }
; #define MFMA32(a, b, c) __builtin_amdgcn_mfma_f32_32x32x16_bf16((a), (b), (c), 0, 0, 0)
; #define SBAR() __builtin_amdgcn_sched_barrier(0)
; template <int VSTR, int NDVB> DI void pv64(f32x16 (&O)[NDVB], const lds8* vp, const bf16x8 (&P)[4]) {
;   bf16x8 f[2][NDVB];
; #pragma unroll
;   for (int d = 0; d < NDVB; ++d) { const s16x4 lo = trrd(vp + d * 64), hi = trrd(vp + 8 * VSTR + d * 64); f[0][d] = __builtin_shufflevector(lo, hi, 0, 1, 2, 3, 4, 5, 6, 7); }
; #pragma unroll
;   for (int kk = 0; kk < 4; ++kk) {
;     if (kk < 3) {
; #pragma unroll
;       for (int d = 0; d < NDVB; ++d) { const s16x4 lo = trrd(vp + (16 * (kk + 1)) * VSTR + d * 64), hi = trrd(vp + (16 * (kk + 1) + 8) * VSTR + d * 64);
;         f[(kk + 1) & 1][d] = __builtin_shufflevector(lo, hi, 0, 1, 2, 3, 4, 5, 6, 7); }
;     }
;     SBAR();
;     __builtin_amdgcn_s_setprio(1);
; #pragma unroll
;     for (int d = 0; d < NDVB; ++d) O[d] = MFMA32(f[kk & 1][d], P[kk], O[d]);
;     __builtin_amdgcn_s_setprio(0);
;     SBAR();
;   }
; }
; template <int NDVB, bool HAS_NEXT> DI void softmax_def(f32x16& sa0, f32x16& sa1, f32x16& sb0, f32x16& sb1, f32x16 (&O)[NDVB], float& muse, float& l, bool first, bf16x8 (&P)[4], bool check = true) {
;     ...
;   float sum = 0.f;
; #pragma unroll
;   for (int i = 0; i < 16; ++i) { sa0[i] = __builtin_amdgcn_exp2f(sa0[i]); sum += sa0[i]; }
; #pragma unroll
;   for (int i = 0; i < 16; ++i) { sa1[i] = __builtin_amdgcn_exp2f(sa1[i]); sum += sa1[i]; }
;   l += sum;
;   u32x4 w;
;   w.x = cvtpk(sa0[0], sa0[1]); w.y = cvtpk(sa0[2], sa0[3]); w.z = cvtpk(sa0[4], sa0[5]); w.w = cvtpk(sa0[6], sa0[7]); P[0] = __builtin_bit_cast(bf16x8, w);
;   w.x = cvtpk(sa0[8], sa0[9]); w.y = cvtpk(sa0[10], sa0[11]); w.z = cvtpk(sa0[12], sa0[13]); w.w = cvtpk(sa0[14], sa0[15]); P[1] = __builtin_bit_cast(bf16x8, w);
;   w.x = cvtpk(sa1[0], sa1[1]); w.y = cvtpk(sa1[2], sa1[3]); w.z = cvtpk(sa1[4], sa1[5]); w.w = cvtpk(sa1[6], sa1[7]); P[2] = __builtin_bit_cast(bf16x8, w);
;   w.x = cvtpk(sa1[8], sa1[9]); w.y = cvtpk(sa1[10], sa1[11]); w.z = cvtpk(sa1[12], sa1[13]); w.w = cvtpk(sa1[14], sa1[15]); P[3] = __builtin_bit_cast(bf16x8, w);
.LBB0_903:
	v_lshlrev_b32_e32 v217, 3, v55
	v_add_f32_e32 v0, v97, v98
	v_add_f32_e32 v55, v99, v56
	v_add_f32_e32 v121, v0, v55
	v_add_f32_e32 v0, v109, v110
	v_add_f32_e32 v55, v111, v60
	v_add_f32_e32 v97, v0, v55
	v_add_f32_e32 v0, v100, v101
	v_add_f32_e32 v55, v102, v57
	v_add_f32_e32 v101, v0, v55
	v_add_f32_e32 v0, v112, v113
	v_add_f32_e32 v55, v114, v61
	v_add_f32_e32 v98, v0, v55
	v_add_f32_e32 v0, v103, v104
	v_add_f32_e32 v55, v105, v58
	v_exp_f32_e32 v50, v50
	v_add_f32_e32 v100, v0, v55
	v_add_f32_e32 v0, v115, v116
	v_add_f32_e32 v55, v117, v62
	v_exp_f32_e32 v51, v51
	v_add_f32_e32 v55, v0, v55
	v_add_f32_e32 v0, v106, v107
	v_add_f32_e32 v99, v108, v59
	v_exp_f32_e32 v103, v18
	v_add_f32_e32 v99, v0, v99
	v_add_f32_e32 v0, v118, v119
	v_add_f32_e32 v102, v120, v63
	v_exp_f32_e32 v18, v19
	v_add_f32_e32 v0, v0, v102
	v_add_f32_e32 v102, 0, v50
	v_add_f32_e32 v102, v51, v102
	v_add_f32_e32 v102, v103, v102
	v_add_f32_e32 v19, v18, v102
	v_exp_f32_e32 v102, v20
	v_exp_f32_e32 v21, v21
	v_exp_f32_e32 v22, v22
	v_exp_f32_e32 v104, v2
	v_add_f32_e32 v19, v102, v19
	v_add_f32_e32 v19, v21, v19
	v_add_f32_e32 v20, v22, v19
	v_exp_f32_e32 v19, v23
	v_exp_f32_e32 v23, v24
	v_exp_f32_e32 v24, v25
	v_exp_f32_e32 v25, v26
	v_add_f32_e32 v20, v19, v20
	v_add_f32_e32 v20, v23, v20
	v_add_f32_e32 v20, v24, v20
	v_add_f32_e32 v26, v25, v20
	v_exp_f32_e32 v20, v27
	v_exp_f32_e32 v27, v28
	v_exp_f32_e32 v28, v29
	v_exp_f32_e32 v29, v30
	v_add_f32_e32 v26, v20, v26
	v_exp_f32_e32 v30, v31
	v_add_f32_e32 v26, v27, v26
	v_exp_f32_e32 v31, v16
	v_add_f32_e32 v26, v28, v26
	v_add_f32_e32 v26, v29, v26
	v_add_f32_e32 v26, v30, v26
	v_add_f32_e32 v16, v31, v26
	v_exp_f32_e32 v26, v17
	v_exp_f32_e32 v110, v3
	v_exp_f32_e32 v105, v4
	v_exp_f32_e32 v106, v5
	v_add_f32_e32 v16, v26, v16
	v_add_f32_e32 v2, v104, v16
	v_exp_f32_e32 v107, v6
	v_add_f32_e32 v2, v110, v2
	v_exp_f32_e32 v111, v7
	v_add_f32_e32 v2, v105, v2
	v_exp_f32_e32 v108, v8
	v_add_f32_e32 v2, v106, v2
	v_exp_f32_e32 v109, v9
	v_add_f32_e32 v2, v107, v2
	v_exp_f32_e32 v112, v10
	v_add_f32_e32 v2, v111, v2
	v_exp_f32_e32 v113, v11
	v_add_f32_e32 v2, v108, v2
	v_exp_f32_e32 v114, v12
	v_add_f32_e32 v2, v109, v2
	v_exp_f32_e32 v115, v13
	v_add_f32_e32 v2, v112, v2
	v_exp_f32_e32 v116, v14
	v_add_f32_e32 v2, v113, v2
	v_exp_f32_e32 v117, v15
	v_add_f32_e32 v2, v114, v2
	v_add_f32_e32 v2, v115, v2
	v_add_f32_e32 v2, v116, v2
	v_add_f32_e32 v2, v117, v2
	v_cvt_pk_bf16_f32 v4, v102, v21
	v_cvt_pk_bf16_f32 v5, v22, v19
	v_cvt_pk_bf16_f32 v10, v31, v26
	v_add_f32_e32 v26, v26, v31
	v_add_f32_e32 v31, v110, v104
	v_add_f32_e32 v21, v21, v102
	v_add_f32_e32 v22, v19, v22
	v_add_f32_e32 v48, v48, v2
	v_cvt_pk_bf16_f32 v2, v50, v51
	v_add_f32_e32 v50, v51, v50
	v_add_f32_e32 v51, v18, v103
	v_add_f32_e32 v31, v31, v26
	v_add_f32_e32 v21, v22, v21
	v_add_f32_e32 v22, v106, v105
	v_add_f32_e32 v26, v111, v107
	v_cvt_pk_bf16_f32 v6, v23, v24
	v_add_f32_e32 v50, v51, v50
	v_add_f32_e32 v51, v26, v22
	v_add_f32_e32 v22, v24, v23
	v_add_f32_e32 v23, v20, v25
	v_add_f32_e32 v118, v23, v22
	v_add_f32_e32 v22, v109, v108
	v_add_f32_e32 v23, v113, v112
	v_cvt_pk_bf16_f32 v15, v112, v113
	v_add_f32_e32 v112, v23, v22
	v_add_f32_e32 v22, v28, v27
	v_add_f32_e32 v23, v30, v29
	v_add_f32_e32 v119, v23, v22
	v_add_f32_e32 v22, v115, v114
	v_add_f32_e32 v23, v117, v116
	v_cvt_pk_bf16_f32 v3, v103, v18
	v_cvt_pk_bf16_f32 v7, v25, v20
	v_cvt_pk_bf16_f32 v8, v27, v28
	v_cvt_pk_bf16_f32 v9, v29, v30
	v_cvt_pk_bf16_f32 v11, v104, v110
	v_cvt_pk_bf16_f32 v12, v105, v106
	v_cvt_pk_bf16_f32 v13, v107, v111
	v_cvt_pk_bf16_f32 v14, v108, v109
	v_cvt_pk_bf16_f32 v16, v114, v115
	v_add_f32_e32 v114, v23, v22
	ds_read_b64_tr_b16 v[22:23], v96 offset:27648
	ds_read_b64_tr_b16 v[24:25], v96 offset:28800
	ds_read_b64_tr_b16 v[26:27], v96 offset:27712
	ds_read_b64_tr_b16 v[28:29], v96 offset:28864
	ds_read_b64_tr_b16 v[102:103], v96 offset:29952
	ds_read_b64_tr_b16 v[104:105], v96 offset:31104
	ds_read_b64_tr_b16 v[106:107], v96 offset:30016
	ds_read_b64_tr_b16 v[108:109], v96 offset:31168
	v_cvt_pk_bf16_f32 v17, v116, v117
	s_setprio 1
	s_waitcnt lgkmcnt(6)
	v_mfma_f32_32x32x16_bf16 v[80:95], v[22:25], v[2:5], v[80:95]
	s_waitcnt lgkmcnt(4)
	v_mfma_f32_32x32x16_bf16 v[64:79], v[26:29], v[2:5], v[64:79]
	s_setprio 0
	ds_read_b64_tr_b16 v[2:3], v96 offset:32256
	ds_read_b64_tr_b16 v[4:5], v96 offset:33408
	ds_read_b64_tr_b16 v[22:23], v96 offset:32320
	ds_read_b64_tr_b16 v[24:25], v96 offset:33472
	s_setprio 1
	s_waitcnt lgkmcnt(6)
	v_mfma_f32_32x32x16_bf16 v[80:95], v[102:105], v[6:9], v[80:95]
	s_waitcnt lgkmcnt(4)
	v_mfma_f32_32x32x16_bf16 v[64:79], v[106:109], v[6:9], v[64:79]
	s_setprio 0
	ds_read_b64_tr_b16 v[6:7], v96 offset:34560
	ds_read_b64_tr_b16 v[8:9], v96 offset:35712
	ds_read_b64_tr_b16 v[28:29], v96 offset:35776
	ds_read_b64_tr_b16 v[26:27], v96 offset:34624
	s_setprio 1
	s_waitcnt lgkmcnt(6)
	v_mfma_f32_32x32x16_bf16 v[80:95], v[2:5], v[10:13], v[80:95]
	s_waitcnt lgkmcnt(4)
	v_mfma_f32_32x32x16_bf16 v[64:79], v[22:25], v[10:13], v[64:79]
	s_setprio 0
	s_setprio 1
	s_waitcnt lgkmcnt(2)
	v_mfma_f32_32x32x16_bf16 v[80:95], v[6:9], v[14:17], v[80:95]
	s_waitcnt lgkmcnt(0)
	v_mfma_f32_32x32x16_bf16 v[64:79], v[26:29], v[14:17], v[64:79]
	s_setprio 0
	ds_bpermute_b32 v2, v193, v48
	v_readlane_b32 s1, v255, 39
	s_waitcnt lgkmcnt(0)
	s_barrier
; #define LAS __attribute__((address_space(3)))
; DI void nsa_unit(const Params& p, lds8* lds, int bl, int g, int qb32) {
;     ...
;   const float lt0 = l + __shfl_xor(l, 32); const float inv0 = lt0 > 0.f ? 1.f / lt0 : 0.f;
;   { const float f = g0 * inv0;
; #pragma unroll
;     for (int d = 0; d < 2; ++d)
; #pragma unroll
;       for (int i = 0; i < 16; ++i) OT[d][i] = O[d][i] * f; }
;   { LAS float* impw = (LAS float*)(lds + NS_IMPW) + (wid * 32 + r) * 33;
;     float carry = 0.f;
; #pragma unroll
;     for (int kt = 0; kt < 2; ++kt) {
;       const float scale = __builtin_amdgcn_exp2f(cap.mrec[kt] - m) * inv0;
; #pragma unroll
;       for (int kb = 0; kb < 2; ++kb)
; #pragma unroll
;         for (int ii = 0; ii < 4; ++ii) {
;           const float qsum = cap.qs[kt][kb * 4 + ii] * scale, last = cap.ls[kt][kb * 4 + ii] * scale;
;           const float other = __shfl_xor(last, 32);
;           const int ub = 16 * kt + 8 * kb + 2 * ii;
;           const float val = qsum + (h ? other : carry);
;           carry = other;
;           impw[ub + h] = val;
;         }
;     }
;   }
;   __syncthreads();
; #pragma unroll
;   for (int ks = 0; ks < 2; ++ks) {
;     const float* rc = rope + qpos * 32 + 16 * ks + 8 * h;
;     const f32x4 c0 = *(const f32x4*)rc, c1 = *(const f32x4*)(rc + 4), s0 = *(const f32x4*)(rc + 65536), s1 = *(const f32x4*)(rc + 65536 + 4);
	v_add_f32_e32 v2, v48, v2
	v_div_scale_f32 v3, s[8:9], v2, v2, 1.0
	v_rcp_f32_e32 v4, v3
	v_div_scale_f32 v5, vcc, 1.0, v2, 1.0
	v_readlane_b32 s8, v254, 63
	v_fma_f32 v6, -v3, v4, 1.0
	v_fmac_f32_e32 v4, v6, v4
	v_mul_f32_e32 v6, v5, v4
	v_fma_f32 v7, -v3, v6, v5
	v_fmac_f32_e32 v6, v7, v4
	v_fma_f32 v3, -v3, v6, v5
	v_div_fmas_f32 v3, v3, v4, v6
	v_sub_f32_e32 v4, v49, v1
	v_exp_f32_e32 v4, v4
	v_div_fixup_f32 v3, v3, v2, 1.0
	v_cmp_lt_f32_e32 vcc, 0, v2
	v_lshl_or_b32 v2, s1, 5, v52
	v_mul_lo_u32 v2, v2, s94
	v_cndmask_b32_e32 v218, 0, v3, vcc
	v_mul_f32_e32 v3, v4, v218
	v_mul_f32_e32 v4, v56, v3
	v_mul_f32_e32 v5, v57, v3
	ds_bpermute_b32 v4, v193, v4
	ds_bpermute_b32 v5, v193, v5
	v_mul_f32_e32 v7, v58, v3
	v_mul_f32_e32 v8, v59, v3
	ds_bpermute_b32 v7, v193, v7
	ds_bpermute_b32 v8, v193, v8
	v_cmp_gt_u32_e32 vcc, 32, v199
	v_add3_u32 v2, 0, v2, v214
	v_add_u32_e32 v2, 0xd800, v2
	s_waitcnt lgkmcnt(3)
	v_cndmask_b32_e64 v6, v4, 0, vcc
	s_waitcnt lgkmcnt(2)
	v_cndmask_b32_e32 v4, v5, v4, vcc
	v_fmac_f32_e32 v6, v121, v3
	v_fmac_f32_e32 v4, v101, v3
	ds_write2_b32 v2, v6, v4 offset1:2
	s_waitcnt lgkmcnt(2)
	v_cndmask_b32_e32 v4, v7, v5, vcc
	s_waitcnt lgkmcnt(1)
	v_cndmask_b32_e32 v5, v8, v7, vcc
	v_mul_f32_e32 v6, v60, v3
	v_mul_f32_e32 v7, v61, v3
	ds_bpermute_b32 v6, v193, v6
	ds_bpermute_b32 v7, v193, v7
	v_fmac_f32_e32 v4, v100, v3
	v_fmac_f32_e32 v5, v99, v3
	ds_write2_b32 v2, v4, v5 offset0:4 offset1:6
	s_waitcnt lgkmcnt(2)
	v_cndmask_b32_e32 v4, v6, v8, vcc
	s_waitcnt lgkmcnt(1)
	v_cndmask_b32_e32 v5, v7, v6, vcc
	v_fmac_f32_e32 v4, v97, v3
	v_fmac_f32_e32 v5, v98, v3
	ds_write2_b32 v2, v4, v5 offset0:8 offset1:10
	v_mul_f32_e32 v4, v62, v3
	v_sub_f32_e32 v1, v1, v1
	ds_bpermute_b32 v4, v193, v4
	v_exp_f32_e32 v1, v1
	v_mul_f32_e32 v5, v63, v3
	ds_bpermute_b32 v5, v193, v5
	v_lshlrev_b32_e32 v186, 5, v211
	v_mul_f32_e32 v1, v1, v218
	s_waitcnt lgkmcnt(1)
	v_cndmask_b32_e32 v6, v4, v7, vcc
	v_mul_f32_e32 v7, v18, v1
	ds_bpermute_b32 v7, v193, v7
	s_waitcnt lgkmcnt(1)
	v_cndmask_b32_e32 v4, v5, v4, vcc
	v_mul_f32_e32 v8, v19, v1
	v_fmac_f32_e32 v6, v55, v3
	ds_bpermute_b32 v8, v193, v8
	v_fmac_f32_e32 v4, v0, v3
	ds_write2_b32 v2, v6, v4 offset0:12 offset1:14
	s_waitcnt lgkmcnt(2)
	v_cndmask_b32_e32 v0, v7, v5, vcc
	v_mul_f32_e32 v4, v20, v1
	v_mul_f32_e32 v5, v30, v1
	ds_bpermute_b32 v4, v193, v4
	ds_bpermute_b32 v5, v193, v5
	s_waitcnt lgkmcnt(3)
	v_cndmask_b32_e32 v3, v8, v7, vcc
	v_fmac_f32_e32 v0, v50, v1
	v_fmac_f32_e32 v3, v21, v1
	ds_write2_b32 v2, v0, v3 offset0:16 offset1:18
	s_waitcnt lgkmcnt(2)
	v_cndmask_b32_e32 v0, v4, v8, vcc
	s_waitcnt lgkmcnt(1)
	v_cndmask_b32_e32 v3, v5, v4, vcc
	v_mul_f32_e32 v4, v110, v1
	v_mul_f32_e32 v6, v111, v1
	ds_bpermute_b32 v4, v193, v4
	ds_bpermute_b32 v6, v193, v6
	v_fmac_f32_e32 v0, v118, v1
	v_fmac_f32_e32 v3, v119, v1
	ds_write2_b32 v2, v0, v3 offset0:20 offset1:22
	s_waitcnt lgkmcnt(2)
	v_cndmask_b32_e32 v0, v4, v5, vcc
	s_waitcnt lgkmcnt(1)
	v_cndmask_b32_e32 v3, v6, v4, vcc
	v_mul_f32_e32 v4, v113, v1
	v_mul_f32_e32 v5, v117, v1
	ds_bpermute_b32 v4, v193, v4
	ds_bpermute_b32 v5, v193, v5
	v_fmac_f32_e32 v0, v31, v1
	v_fmac_f32_e32 v3, v51, v1
	ds_write2_b32 v2, v0, v3 offset0:24 offset1:26
	s_waitcnt lgkmcnt(2)
	v_cndmask_b32_e32 v0, v4, v6, vcc
	s_waitcnt lgkmcnt(1)
	v_cndmask_b32_e32 v3, v5, v4, vcc
	v_fmac_f32_e32 v0, v112, v1
	v_fmac_f32_e32 v3, v114, v1
	v_readlane_b32 s9, v253, 0
	ds_write2_b32 v2, v0, v3 offset0:28 offset1:30
	s_waitcnt lgkmcnt(0)
	v_lshl_add_u64 v[0:1], v[186:187], 2, s[8:9]
	v_lshlrev_b32_e32 v186, 2, v217
	v_lshl_add_u64 v[4:5], v[0:1], 0, v[186:187]
	s_mov_b64 s[8:9], 0x40000
	v_add_co_u32_e32 v6, vcc, 0x40000, v4
	v_lshl_add_u64 v[0:1], v[4:5], 0, s[8:9]
	s_nop 0
	v_addc_co_u32_e32 v7, vcc, 0, v5, vcc
	s_barrier
	global_load_dwordx4 v[16:19], v[4:5], off offset:16
	global_load_dwordx4 v[24:27], v[4:5], off
	global_load_dwordx4 v[28:31], v[6:7], off
	global_load_dwordx4 v[20:23], v[0:1], off offset:16
	s_nop 0
	global_load_dwordx4 v[0:3], v[4:5], off offset:80
	global_load_dwordx4 v[8:11], v[4:5], off offset:64
	s_mov_b64 s[8:9], 0x40040
	v_lshl_add_u64 v[4:5], v[4:5], 0, s[8:9]
	global_load_dwordx4 v[12:15], v[6:7], off offset:64
	s_nop 0
	global_load_dwordx4 v[4:7], v[4:5], off offset:16
	s_lshl_b32 s10, s71, 20
	v_readlane_b32 s1, v254, 53
	s_add_u32 s11, s1, s10
	v_readlane_b32 s1, v254, 54
	s_addc_u32 s12, s1, 0
	s_lshl_b32 s13, s70, 7
	s_add_u32 s78, s11, s13
	s_addc_u32 s79, s12, 0
	v_readlane_b32 s1, v254, 59
	s_add_u32 s10, s1, s10
	v_readlane_b32 s1, v254, 60
	s_addc_u32 s11, s1, 0
	s_add_u32 s80, s10, s13
	s_addc_u32 s81, s11, 0
	s_lshr_b32 s6, s3, 1
	s_add_i32 s6, s6, -8
	s_max_i32 s6, s6, 0
	v_lshl_add_u32 v250, s6, 6, v212
	v_lshlrev_b32_e32 v250, 9, v250
	v_add_u32_e32 v250, v250, v192
	v_add_u32_e32 v251, 0x8000, v250
	global_load_dwordx4 v[236:239], v250, s[78:79] offset:256
	global_load_dwordx4 v[240:243], v250, s[80:81] offset:256
	global_load_dwordx4 v[244:247], v251, s[78:79] offset:256
	global_load_dwordx4 v[248:251], v251, s[80:81] offset:256
	v_lshl_add_u32 v132, v212, 9, v192
	global_load_dwordx4 v[128:131], v132, s[78:79]
	global_load_dwordx4 v[132:135], v132, s[80:81]
	v_cmp_eq_u32_e32 vcc, 0, v136
	s_and_saveexec_b64 s[8:9], vcc
	s_cbranch_execz .LBB0_905
	v_readlane_b32 s1, v255, 10
	s_nop 1
	v_mov_b32_e32 v48, s1
	ds_write_b32 v48, v187

; #define NS_GLOAD(k_, KR, VR) do { const int jj = __builtin_amdgcn_readfirstlane(jl[(k_)]); KR = *(const u32x4*)(kg + (size_t)(64 * jj + sr) * pitch + sc * 8); VR = *(const u32x4*)(vg + (size_t)(64 * jj + sr) * pitch + sc * 8); } while (0)
; #define NS_LSTORE(st_, KR, VR) do { lds8* b = lds + (st_) * NS_STAGE; *(LAS u32x4*)(b + sr * NS_STR + sc * 16) = KR; *(LAS u32x4*)(b + 64 * NS_STR + sr * NS_STR + sc * 16) = VR; } while (0)
; template <int MODE>
; DI void nsa_branch(lds8* lds, const bf16_t* kg, const bf16_t* vg, int pitch, unsigned tiles, const bf16x8 (&q)[4], int qpos, unsigned mybits, int blk,
;                    f32x16 (&O)[2], float& muse, float& l, int tid, int lane, int grp, CmpCap& cap) {
;     ...
;   NS_GLOAD(0, kra, vra); NS_LSTORE(0, kra, vra);
;   if (ntl > 1) { NS_GLOAD(1, kra, vra); NS_LSTORE(1, kra, vra); }
;   __syncthreads();
.LBB0_932:
	s_or_b64 exec, exec, s[10:11]
	s_lshl_b32 s10, s71, 20
	v_readlane_b32 s1, v254, 53
	s_add_u32 s11, s1, s10
	v_readlane_b32 s1, v254, 54
	v_mov_b32_e32 v48, s0
	s_addc_u32 s12, s1, 0
	s_lshl_b32 s13, s70, 7
	s_waitcnt lgkmcnt(0)
	s_barrier
	ds_read_b32 v48, v48
	s_add_u32 s78, s11, s13
	s_addc_u32 s79, s12, 0
	v_readlane_b32 s1, v254, 59
	s_add_u32 s10, s1, s10
	v_readlane_b32 s1, v254, 60
	s_addc_u32 s11, s1, 0
	s_add_u32 s80, s10, s13
	s_addc_u32 s81, s11, 0
	v_readlane_b32 s1, v255, 9
	v_lshlrev_b32_e32 v186, 1, v54
	s_bcnt1_i32_b32 s88, s6
	v_mov_b32_e32 v112, s1
	ds_read_b32 v112, v112
	s_waitcnt lgkmcnt(0)
	v_readfirstlane_b32 s10, v48
	v_readfirstlane_b32 s11, v112
	s_nop 1
	v_lshl_add_u32 v48, s10, 6, v212
	v_lshl_add_u32 v112, s11, 6, v212
	v_ashrrev_i32_e32 v49, 31, v48
	v_lshlrev_b64 v[48:49], 9, v[48:49]
	v_lshl_add_u64 v[50:51], s[78:79], 0, v[48:49]
	v_lshl_add_u64 v[50:51], v[50:51], 0, v[186:187]
	v_lshl_add_u64 v[48:49], s[80:81], 0, v[48:49]
	v_lshl_add_u64 v[48:49], v[48:49], 0, v[186:187]
	s_cmp_lt_u32 s88, 2
	s_cbranch_scc1 .Lslc_pro_one
	v_ashrrev_i32_e32 v113, 31, v112
	v_lshlrev_b64 v[112:113], 9, v[112:113]
	v_lshl_add_u64 v[50:51], s[78:79], 0, v[112:113]
	v_lshl_add_u64 v[48:49], s[80:81], 0, v[112:113]
	v_lshl_add_u64 v[50:51], v[50:51], 0, v[186:187]
	v_lshl_add_u64 v[48:49], v[48:49], 0, v[186:187]
	global_load_dwordx4 v[112:115], v[50:51], off
	global_load_dwordx4 v[116:119], v[48:49], off
	s_waitcnt vmcnt(3)
	ds_write_b128 v215, v[128:131]
	s_waitcnt vmcnt(2)
	ds_write_b128 v215, v[132:135] offset:9216
	s_waitcnt vmcnt(1)
	ds_write_b128 v215, v[112:115] offset:18432
	s_waitcnt vmcnt(0)
	ds_write_b128 v215, v[116:119] offset:27648
	s_branch .LBB0_934
